# in-proj epilogue RoPE rows: rope-table prefetch one row-group ahead with counted vmcnt that leaves the previous group's store and the next prefetch in flight
# speedup vs baseline: 1.0019x; 1.0008x over previous
;   DI void operator()(int mt, int nt, int wm, int wn, int r, int h, f32x16 (&acc)[WM][2]) const {
;     ...
;           if (ropemode != 0) {
;             const int pc = (ropemode == 1) ? (cc ^ 1) : (cc ^ 2);
;             const float4 p0 = *(const float4*)(T + lr * LD + pc * 8), p1 = *(const float4*)(T + lr * LD + pc * 8 + 4);
;             const float4 c0 = *(const float4*)(bias + nt * 128 + pc * 8), c1 = *(const float4*)(bias + nt * 128 + pc * 8 + 4);
;             const float pr[8] = {p0.x + c0.x, p0.y + c0.y, p0.z + c0.z, p0.w + c0.w, p1.x + c1.x, p1.y + c1.y, p1.z + c1.z, p1.w + c1.w};
;             const int tok = t - NCTX;
;             const int q = (ropemode == 1) ? (cc & 3) : ((cc & 7) >> 1);
;             const int pos = (q < 2) ? (tok >> 6) : (tok & 63);
;             const float2* tab = (ropemode == 1) ? (T32 + pos * 8) : (T64 + pos * 16 + (cc & 1) * 8);
;             const float sgn = (q & 1) ? 1.f : -1.f;
; #pragma unroll
;             for (int k = 0; k < 8; ++k) { const float2 cs = tab[k]; v[k] = v[k] * cs.x + sgn * pr[k] * cs.y; }
.Lrp_l_0_1:
	global_load_dwordx4 v[228:231], v[120:121], off
	global_load_dwordx4 v[232:235], v[120:121], off offset:16
	global_load_dwordx4 v[236:239], v[120:121], off offset:32
	global_load_dwordx4 v[240:243], v[120:121], off offset:48
	s_waitcnt vmcnt(5) lgkmcnt(1)
	v_add_f32_e32 v80, v84, v213
	v_add_f32_e32 v81, v85, v218
	v_add_f32_e32 v84, v86, v219
	v_add_f32_e32 v85, v87, v245
	s_waitcnt lgkmcnt(0)
	v_add_f32_e32 v86, v76, v250
	v_add_f32_e32 v87, v77, v251
	v_add_f32_e32 v91, v78, v126
	v_add_f32_e32 v96, v79, v127
	v_mov_b32_e32 v72, v112
	v_mov_b32_e32 v73, v113
	v_mov_b32_e32 v74, v114
	v_mov_b32_e32 v75, v115
	v_mov_b32_e32 v79, v69
	v_cndmask_b32_e64 v78, v80, -v80, s[0:1]
	v_cndmask_b32_e64 v84, v84, -v84, s[0:1]
	v_cndmask_b32_e64 v86, v86, -v86, s[0:1]
	s_waitcnt vmcnt(5) lgkmcnt(0)
	v_mov_b32_e32 v76, v73
	v_cndmask_b32_e64 v73, v81, -v81, s[0:1]
	v_mov_b32_e32 v69, v73
	v_mov_b32_e32 v73, v75
	v_mov_b32_e32 v77, v74
	v_pk_mul_f32 v[80:81], v[68:69], v[72:73]
	v_mov_b32_e32 v72, v116
	v_mov_b32_e32 v73, v117
	v_mov_b32_e32 v74, v118
	v_mov_b32_e32 v75, v119
	v_cndmask_b32_e64 v68, v85, -v85, s[0:1]
	v_mov_b32_e32 v85, v71
	v_mov_b32_e32 v71, v68
	s_waitcnt vmcnt(5) lgkmcnt(0)
	v_mov_b32_e32 v82, v73
	v_mov_b32_e32 v73, v75
	v_pk_mul_f32 v[72:73], v[70:71], v[72:73]
	v_mov_b32_e32 v68, v214
	v_mov_b32_e32 v69, v215
	v_mov_b32_e32 v70, v216
	v_mov_b32_e32 v71, v217
	v_mov_b32_e32 v83, v74
	s_waitcnt vmcnt(5) lgkmcnt(0)
	v_mov_b32_e32 v74, v69
	v_cndmask_b32_e64 v69, v87, -v87, s[0:1]
	v_mov_b32_e32 v87, v65
	v_mov_b32_e32 v65, v69
	v_mov_b32_e32 v69, v71
	v_mov_b32_e32 v75, v70
	v_pk_mul_f32 v[64:65], v[64:65], v[68:69]
	v_mov_b32_e32 v68, v246
	v_mov_b32_e32 v69, v247
	v_mov_b32_e32 v70, v248
	v_mov_b32_e32 v71, v249
	v_pk_fma_f32 v[64:65], v[86:87], v[74:75], v[64:65]
	s_waitcnt vmcnt(5) lgkmcnt(0)
	v_mul_f32_e32 v66, v66, v68
	v_cndmask_b32_e64 v68, v91, -v91, s[0:1]
	v_mul_f32_e32 v92, v68, v69
	v_cndmask_b32_e64 v69, v96, -v96, s[0:1]
	v_mov_b32_e32 v68, v67
	v_pk_mul_f32 v[68:69], v[68:69], v[70:71]
	v_pk_fma_f32 v[70:71], v[84:85], v[82:83], v[72:73]
	v_mov_b32_e32 v67, v68
	v_mov_b32_e32 v93, v69
	v_pk_fma_f32 v[68:69], v[78:79], v[76:77], v[80:81]
	v_pk_add_f32 v[66:67], v[66:67], v[92:93]

;   DI void operator()(int mt, int nt, int wm, int wn, int r, int h, f32x16 (&acc)[WM][2]) const {
;     ...
;           if (ropemode != 0) {
;             const int pc = (ropemode == 1) ? (cc ^ 1) : (cc ^ 2);
;             const float4 p0 = *(const float4*)(T + lr * LD + pc * 8), p1 = *(const float4*)(T + lr * LD + pc * 8 + 4);
;             const float4 c0 = *(const float4*)(bias + nt * 128 + pc * 8), c1 = *(const float4*)(bias + nt * 128 + pc * 8 + 4);
;             const float pr[8] = {p0.x + c0.x, p0.y + c0.y, p0.z + c0.z, p0.w + c0.w, p1.x + c1.x, p1.y + c1.y, p1.z + c1.z, p1.w + c1.w};
;             const int tok = t - NCTX;
;             const int q = (ropemode == 1) ? (cc & 3) : ((cc & 7) >> 1);
;             const int pos = (q < 2) ? (tok >> 6) : (tok & 63);
;             const float2* tab = (ropemode == 1) ? (T32 + pos * 8) : (T64 + pos * 16 + (cc & 1) * 8);
;             const float sgn = (q & 1) ? 1.f : -1.f;
; #pragma unroll
;             for (int k = 0; k < 8; ++k) { const float2 cs = tab[k]; v[k] = v[k] * cs.x + sgn * pr[k] * cs.y; }
.Lrp_l_0_2:
	global_load_dwordx4 v[112:115], v[120:121], off
	global_load_dwordx4 v[116:119], v[120:121], off offset:16
	global_load_dwordx4 v[214:217], v[120:121], off offset:32
	global_load_dwordx4 v[246:249], v[120:121], off offset:48
	s_waitcnt vmcnt(5) lgkmcnt(1)
	v_add_f32_e32 v80, v84, v213
	v_add_f32_e32 v81, v85, v218
	v_add_f32_e32 v84, v86, v219
	v_add_f32_e32 v85, v87, v245
	s_waitcnt lgkmcnt(0)
	v_add_f32_e32 v86, v76, v250
	v_add_f32_e32 v87, v77, v251
	v_add_f32_e32 v91, v78, v126
	v_add_f32_e32 v97, v79, v127
	v_mov_b32_e32 v72, v228
	v_mov_b32_e32 v73, v229
	v_mov_b32_e32 v74, v230
	v_mov_b32_e32 v75, v231
	v_mov_b32_e32 v79, v69
	v_cndmask_b32_e64 v78, v80, -v80, s[0:1]
	v_cndmask_b32_e64 v84, v84, -v84, s[0:1]
	v_cndmask_b32_e64 v86, v86, -v86, s[0:1]
	s_waitcnt vmcnt(5) lgkmcnt(0)
	v_mov_b32_e32 v76, v73
	v_cndmask_b32_e64 v73, v81, -v81, s[0:1]
	v_mov_b32_e32 v69, v73
	v_mov_b32_e32 v73, v75
	v_mov_b32_e32 v77, v74
	v_pk_mul_f32 v[80:81], v[68:69], v[72:73]
	v_mov_b32_e32 v72, v232
	v_mov_b32_e32 v73, v233
	v_mov_b32_e32 v74, v234
	v_mov_b32_e32 v75, v235
	v_cndmask_b32_e64 v68, v85, -v85, s[0:1]
	v_mov_b32_e32 v85, v71
	v_mov_b32_e32 v71, v68
	s_waitcnt vmcnt(5) lgkmcnt(0)
	v_mov_b32_e32 v82, v73
	v_mov_b32_e32 v73, v75
	v_pk_mul_f32 v[72:73], v[70:71], v[72:73]
	v_mov_b32_e32 v68, v236
	v_mov_b32_e32 v69, v237
	v_mov_b32_e32 v70, v238
	v_mov_b32_e32 v71, v239
	v_mov_b32_e32 v83, v74
	s_waitcnt vmcnt(5) lgkmcnt(0)
	v_mov_b32_e32 v74, v69
	v_cndmask_b32_e64 v69, v87, -v87, s[0:1]
	v_mov_b32_e32 v87, v65
	v_mov_b32_e32 v65, v69
	v_mov_b32_e32 v69, v71
	v_mov_b32_e32 v75, v70
	v_pk_mul_f32 v[64:65], v[64:65], v[68:69]
	v_mov_b32_e32 v68, v240
	v_mov_b32_e32 v69, v241
	v_mov_b32_e32 v70, v242
	v_mov_b32_e32 v71, v243
	v_pk_fma_f32 v[64:65], v[86:87], v[74:75], v[64:65]
	s_waitcnt vmcnt(5) lgkmcnt(0)
	v_mul_f32_e32 v66, v66, v68
	v_cndmask_b32_e64 v68, v91, -v91, s[0:1]
	v_mul_f32_e32 v92, v68, v69
	v_cndmask_b32_e64 v69, v97, -v97, s[0:1]
	v_mov_b32_e32 v68, v67
	v_pk_mul_f32 v[68:69], v[68:69], v[70:71]
	v_pk_fma_f32 v[70:71], v[84:85], v[82:83], v[72:73]
	v_mov_b32_e32 v67, v68
	v_mov_b32_e32 v93, v69
	v_pk_fma_f32 v[68:69], v[78:79], v[76:77], v[80:81]
	v_pk_add_f32 v[66:67], v[66:67], v[92:93]

;   DI void operator()(int mt, int nt, int wm, int wn, int r, int h, f32x16 (&acc)[WM][2]) const {
;     ...
;           if (ropemode != 0) {
;             const int pc = (ropemode == 1) ? (cc ^ 1) : (cc ^ 2);
;             const float4 p0 = *(const float4*)(T + lr * LD + pc * 8), p1 = *(const float4*)(T + lr * LD + pc * 8 + 4);
;             const float4 c0 = *(const float4*)(bias + nt * 128 + pc * 8), c1 = *(const float4*)(bias + nt * 128 + pc * 8 + 4);
;             const float pr[8] = {p0.x + c0.x, p0.y + c0.y, p0.z + c0.z, p0.w + c0.w, p1.x + c1.x, p1.y + c1.y, p1.z + c1.z, p1.w + c1.w};
;             const int tok = t - NCTX;
;             const int q = (ropemode == 1) ? (cc & 3) : ((cc & 7) >> 1);
;             const int pos = (q < 2) ? (tok >> 6) : (tok & 63);
;             const float2* tab = (ropemode == 1) ? (T32 + pos * 8) : (T64 + pos * 16 + (cc & 1) * 8);
;             const float sgn = (q & 1) ? 1.f : -1.f;
; #pragma unroll
;             for (int k = 0; k < 8; ++k) { const float2 cs = tab[k]; v[k] = v[k] * cs.x + sgn * pr[k] * cs.y; }
.Lrp_l_0_3:
	global_load_dwordx4 v[228:231], v[120:121], off
	global_load_dwordx4 v[232:235], v[120:121], off offset:16
	global_load_dwordx4 v[236:239], v[120:121], off offset:32
	global_load_dwordx4 v[240:243], v[120:121], off offset:48
	s_waitcnt vmcnt(5) lgkmcnt(1)
	v_add_f32_e32 v80, v84, v213
	v_add_f32_e32 v81, v85, v218
	v_add_f32_e32 v84, v86, v219
	v_add_f32_e32 v85, v87, v245
	s_waitcnt lgkmcnt(0)
	v_add_f32_e32 v86, v76, v250
	v_add_f32_e32 v87, v77, v251
	v_add_f32_e32 v91, v78, v126
	v_add_f32_e32 v98, v79, v127
	v_mov_b32_e32 v72, v112
	v_mov_b32_e32 v73, v113
	v_mov_b32_e32 v74, v114
	v_mov_b32_e32 v75, v115
	v_mov_b32_e32 v79, v69
	v_cndmask_b32_e64 v78, v80, -v80, s[0:1]
	v_cndmask_b32_e64 v84, v84, -v84, s[0:1]
	v_cndmask_b32_e64 v86, v86, -v86, s[0:1]
	s_waitcnt vmcnt(5) lgkmcnt(0)
	v_mov_b32_e32 v76, v73
	v_cndmask_b32_e64 v73, v81, -v81, s[0:1]
	v_mov_b32_e32 v69, v73
	v_mov_b32_e32 v73, v75
	v_mov_b32_e32 v77, v74
	v_pk_mul_f32 v[80:81], v[68:69], v[72:73]
	v_mov_b32_e32 v72, v116
	v_mov_b32_e32 v73, v117
	v_mov_b32_e32 v74, v118
	v_mov_b32_e32 v75, v119
	v_cndmask_b32_e64 v68, v85, -v85, s[0:1]
	v_mov_b32_e32 v85, v71
	v_mov_b32_e32 v71, v68
	s_waitcnt vmcnt(5) lgkmcnt(0)
	v_mov_b32_e32 v82, v73
	v_mov_b32_e32 v73, v75
	v_pk_mul_f32 v[72:73], v[70:71], v[72:73]
	v_mov_b32_e32 v68, v214
	v_mov_b32_e32 v69, v215
	v_mov_b32_e32 v70, v216
	v_mov_b32_e32 v71, v217
	v_mov_b32_e32 v83, v74
	s_waitcnt vmcnt(5) lgkmcnt(0)
	v_mov_b32_e32 v74, v69
	v_cndmask_b32_e64 v69, v87, -v87, s[0:1]
	v_mov_b32_e32 v87, v65
	v_mov_b32_e32 v65, v69
	v_mov_b32_e32 v69, v71
	v_mov_b32_e32 v75, v70
	v_pk_mul_f32 v[64:65], v[64:65], v[68:69]
	v_mov_b32_e32 v68, v246
	v_mov_b32_e32 v69, v247
	v_mov_b32_e32 v70, v248
	v_mov_b32_e32 v71, v249
	v_pk_fma_f32 v[64:65], v[86:87], v[74:75], v[64:65]
	s_waitcnt vmcnt(5) lgkmcnt(0)
	v_mul_f32_e32 v66, v66, v68
	v_cndmask_b32_e64 v68, v91, -v91, s[0:1]
	v_mul_f32_e32 v92, v68, v69
	v_cndmask_b32_e64 v69, v98, -v98, s[0:1]
	v_mov_b32_e32 v68, v67
	v_pk_mul_f32 v[68:69], v[68:69], v[70:71]
	v_pk_fma_f32 v[70:71], v[84:85], v[82:83], v[72:73]
	v_mov_b32_e32 v67, v68
	v_mov_b32_e32 v93, v69
	v_pk_fma_f32 v[68:69], v[78:79], v[76:77], v[80:81]
	v_pk_add_f32 v[66:67], v[66:67], v[92:93]

;   DI void operator()(int mt, int nt, int wm, int wn, int r, int h, f32x16 (&acc)[WM][2]) const {
;     ...
;           if (ropemode != 0) {
;             const int pc = (ropemode == 1) ? (cc ^ 1) : (cc ^ 2);
;             const float4 p0 = *(const float4*)(T + lr * LD + pc * 8), p1 = *(const float4*)(T + lr * LD + pc * 8 + 4);
;             const float4 c0 = *(const float4*)(bias + nt * 128 + pc * 8), c1 = *(const float4*)(bias + nt * 128 + pc * 8 + 4);
;             const float pr[8] = {p0.x + c0.x, p0.y + c0.y, p0.z + c0.z, p0.w + c0.w, p1.x + c1.x, p1.y + c1.y, p1.z + c1.z, p1.w + c1.w};
;             const int tok = t - NCTX;
;             const int q = (ropemode == 1) ? (cc & 3) : ((cc & 7) >> 1);
;             const int pos = (q < 2) ? (tok >> 6) : (tok & 63);
;             const float2* tab = (ropemode == 1) ? (T32 + pos * 8) : (T64 + pos * 16 + (cc & 1) * 8);
;             const float sgn = (q & 1) ? 1.f : -1.f;
; #pragma unroll
;             for (int k = 0; k < 8; ++k) { const float2 cs = tab[k]; v[k] = v[k] * cs.x + sgn * pr[k] * cs.y; }
.Lrp_l_0_4:
	global_load_dwordx4 v[112:115], v[120:121], off
	global_load_dwordx4 v[116:119], v[120:121], off offset:16
	global_load_dwordx4 v[214:217], v[120:121], off offset:32
	global_load_dwordx4 v[246:249], v[120:121], off offset:48
	s_waitcnt vmcnt(5) lgkmcnt(1)
	v_add_f32_e32 v80, v84, v213
	v_add_f32_e32 v81, v85, v218
	v_add_f32_e32 v84, v86, v219
	v_add_f32_e32 v85, v87, v245
	s_waitcnt lgkmcnt(0)
	v_add_f32_e32 v86, v76, v250
	v_add_f32_e32 v87, v77, v251
	v_add_f32_e32 v91, v78, v126
	v_add_f32_e32 v99, v79, v127
	v_mov_b32_e32 v72, v228
	v_mov_b32_e32 v73, v229
	v_mov_b32_e32 v74, v230
	v_mov_b32_e32 v75, v231
	v_mov_b32_e32 v79, v69
	v_cndmask_b32_e64 v78, v80, -v80, s[0:1]
	v_cndmask_b32_e64 v84, v84, -v84, s[0:1]
	v_cndmask_b32_e64 v86, v86, -v86, s[0:1]
	s_waitcnt vmcnt(5) lgkmcnt(0)
	v_mov_b32_e32 v76, v73
	v_cndmask_b32_e64 v73, v81, -v81, s[0:1]
	v_mov_b32_e32 v69, v73
	v_mov_b32_e32 v73, v75
	v_mov_b32_e32 v77, v74
	v_pk_mul_f32 v[80:81], v[68:69], v[72:73]
	v_mov_b32_e32 v72, v232
	v_mov_b32_e32 v73, v233
	v_mov_b32_e32 v74, v234
	v_mov_b32_e32 v75, v235
	v_cndmask_b32_e64 v68, v85, -v85, s[0:1]
	v_mov_b32_e32 v85, v71
	v_mov_b32_e32 v71, v68
	s_waitcnt vmcnt(5) lgkmcnt(0)
	v_mov_b32_e32 v82, v73
	v_mov_b32_e32 v73, v75
	v_pk_mul_f32 v[72:73], v[70:71], v[72:73]
	v_mov_b32_e32 v68, v236
	v_mov_b32_e32 v69, v237
	v_mov_b32_e32 v70, v238
	v_mov_b32_e32 v71, v239
	v_mov_b32_e32 v83, v74
	s_waitcnt vmcnt(5) lgkmcnt(0)
	v_mov_b32_e32 v74, v69
	v_cndmask_b32_e64 v69, v87, -v87, s[0:1]
	v_mov_b32_e32 v87, v65
	v_mov_b32_e32 v65, v69
	v_mov_b32_e32 v69, v71
	v_mov_b32_e32 v75, v70
	v_pk_mul_f32 v[64:65], v[64:65], v[68:69]
	v_mov_b32_e32 v68, v240
	v_mov_b32_e32 v69, v241
	v_mov_b32_e32 v70, v242
	v_mov_b32_e32 v71, v243
	v_pk_fma_f32 v[64:65], v[86:87], v[74:75], v[64:65]
	s_waitcnt vmcnt(5) lgkmcnt(0)
	v_mul_f32_e32 v66, v66, v68
	v_cndmask_b32_e64 v68, v91, -v91, s[0:1]
	v_mul_f32_e32 v92, v68, v69
	v_cndmask_b32_e64 v69, v99, -v99, s[0:1]
	v_mov_b32_e32 v68, v67
	v_pk_mul_f32 v[68:69], v[68:69], v[70:71]
	v_pk_fma_f32 v[70:71], v[84:85], v[82:83], v[72:73]
	v_mov_b32_e32 v67, v68
	v_mov_b32_e32 v93, v69
	v_pk_fma_f32 v[68:69], v[78:79], v[76:77], v[80:81]
	v_pk_add_f32 v[66:67], v[66:67], v[92:93]

;   DI void operator()(int mt, int nt, int wm, int wn, int r, int h, f32x16 (&acc)[WM][2]) const {
;     ...
;           if (ropemode != 0) {
;             const int pc = (ropemode == 1) ? (cc ^ 1) : (cc ^ 2);
;             const float4 p0 = *(const float4*)(T + lr * LD + pc * 8), p1 = *(const float4*)(T + lr * LD + pc * 8 + 4);
;             const float4 c0 = *(const float4*)(bias + nt * 128 + pc * 8), c1 = *(const float4*)(bias + nt * 128 + pc * 8 + 4);
;             const float pr[8] = {p0.x + c0.x, p0.y + c0.y, p0.z + c0.z, p0.w + c0.w, p1.x + c1.x, p1.y + c1.y, p1.z + c1.z, p1.w + c1.w};
;             const int tok = t - NCTX;
;             const int q = (ropemode == 1) ? (cc & 3) : ((cc & 7) >> 1);
;             const int pos = (q < 2) ? (tok >> 6) : (tok & 63);
;             const float2* tab = (ropemode == 1) ? (T32 + pos * 8) : (T64 + pos * 16 + (cc & 1) * 8);
;             const float sgn = (q & 1) ? 1.f : -1.f;
; #pragma unroll
;             for (int k = 0; k < 8; ++k) { const float2 cs = tab[k]; v[k] = v[k] * cs.x + sgn * pr[k] * cs.y; }
.Lrp_l_0_5:
	global_load_dwordx4 v[228:231], v[120:121], off
	global_load_dwordx4 v[232:235], v[120:121], off offset:16
	global_load_dwordx4 v[236:239], v[120:121], off offset:32
	global_load_dwordx4 v[240:243], v[120:121], off offset:48
	s_waitcnt vmcnt(5) lgkmcnt(1)
	v_add_f32_e32 v80, v84, v213
	v_add_f32_e32 v81, v85, v218
	v_add_f32_e32 v84, v86, v219
	v_add_f32_e32 v85, v87, v245
	s_waitcnt lgkmcnt(0)
	v_add_f32_e32 v86, v76, v250
	v_add_f32_e32 v87, v77, v251
	v_add_f32_e32 v91, v78, v126
	v_add_f32_e32 v100, v79, v127
	v_mov_b32_e32 v72, v112
	v_mov_b32_e32 v73, v113
	v_mov_b32_e32 v74, v114
	v_mov_b32_e32 v75, v115
	v_mov_b32_e32 v79, v69
	v_cndmask_b32_e64 v78, v80, -v80, s[0:1]
	v_cndmask_b32_e64 v84, v84, -v84, s[0:1]
	v_cndmask_b32_e64 v86, v86, -v86, s[0:1]
	s_waitcnt vmcnt(5) lgkmcnt(0)
	v_mov_b32_e32 v76, v73
	v_cndmask_b32_e64 v73, v81, -v81, s[0:1]
	v_mov_b32_e32 v69, v73
	v_mov_b32_e32 v73, v75
	v_mov_b32_e32 v77, v74
	v_pk_mul_f32 v[80:81], v[68:69], v[72:73]
	v_mov_b32_e32 v72, v116
	v_mov_b32_e32 v73, v117
	v_mov_b32_e32 v74, v118
	v_mov_b32_e32 v75, v119
	v_cndmask_b32_e64 v68, v85, -v85, s[0:1]
	v_mov_b32_e32 v85, v71
	v_mov_b32_e32 v71, v68
	s_waitcnt vmcnt(5) lgkmcnt(0)
	v_mov_b32_e32 v82, v73
	v_mov_b32_e32 v73, v75
	v_pk_mul_f32 v[72:73], v[70:71], v[72:73]
	v_mov_b32_e32 v68, v214
	v_mov_b32_e32 v69, v215
	v_mov_b32_e32 v70, v216
	v_mov_b32_e32 v71, v217
	v_mov_b32_e32 v83, v74
	s_waitcnt vmcnt(5) lgkmcnt(0)
	v_mov_b32_e32 v74, v69
	v_cndmask_b32_e64 v69, v87, -v87, s[0:1]
	v_mov_b32_e32 v87, v65
	v_mov_b32_e32 v65, v69
	v_mov_b32_e32 v69, v71
	v_mov_b32_e32 v75, v70
	v_pk_mul_f32 v[64:65], v[64:65], v[68:69]
	v_mov_b32_e32 v68, v246
	v_mov_b32_e32 v69, v247
	v_mov_b32_e32 v70, v248
	v_mov_b32_e32 v71, v249
	v_pk_fma_f32 v[64:65], v[86:87], v[74:75], v[64:65]
	s_waitcnt vmcnt(5) lgkmcnt(0)
	v_mul_f32_e32 v66, v66, v68
	v_cndmask_b32_e64 v68, v91, -v91, s[0:1]
	v_mul_f32_e32 v92, v68, v69
	v_cndmask_b32_e64 v69, v100, -v100, s[0:1]
	v_mov_b32_e32 v68, v67
	v_pk_mul_f32 v[68:69], v[68:69], v[70:71]
	v_pk_fma_f32 v[70:71], v[84:85], v[82:83], v[72:73]
	v_mov_b32_e32 v67, v68
	v_mov_b32_e32 v93, v69
	v_pk_fma_f32 v[68:69], v[78:79], v[76:77], v[80:81]
	v_pk_add_f32 v[66:67], v[66:67], v[92:93]

;   DI void operator()(int mt, int nt, int wm, int wn, int r, int h, f32x16 (&acc)[WM][2]) const {
;     ...
;           if (ropemode != 0) {
;             const int pc = (ropemode == 1) ? (cc ^ 1) : (cc ^ 2);
;             const float4 p0 = *(const float4*)(T + lr * LD + pc * 8), p1 = *(const float4*)(T + lr * LD + pc * 8 + 4);
;             const float4 c0 = *(const float4*)(bias + nt * 128 + pc * 8), c1 = *(const float4*)(bias + nt * 128 + pc * 8 + 4);
;             const float pr[8] = {p0.x + c0.x, p0.y + c0.y, p0.z + c0.z, p0.w + c0.w, p1.x + c1.x, p1.y + c1.y, p1.z + c1.z, p1.w + c1.w};
;             const int tok = t - NCTX;
;             const int q = (ropemode == 1) ? (cc & 3) : ((cc & 7) >> 1);
;             const int pos = (q < 2) ? (tok >> 6) : (tok & 63);
;             const float2* tab = (ropemode == 1) ? (T32 + pos * 8) : (T64 + pos * 16 + (cc & 1) * 8);
;             const float sgn = (q & 1) ? 1.f : -1.f;
; #pragma unroll
;             for (int k = 0; k < 8; ++k) { const float2 cs = tab[k]; v[k] = v[k] * cs.x + sgn * pr[k] * cs.y; }
.Lrp_l_0_6:
	global_load_dwordx4 v[112:115], v[120:121], off
	global_load_dwordx4 v[116:119], v[120:121], off offset:16
	global_load_dwordx4 v[214:217], v[120:121], off offset:32
	global_load_dwordx4 v[246:249], v[120:121], off offset:48
	s_waitcnt vmcnt(5) lgkmcnt(1)
	v_add_f32_e32 v80, v84, v213
	v_add_f32_e32 v81, v85, v218
	v_add_f32_e32 v84, v86, v219
	v_add_f32_e32 v85, v87, v245
	s_waitcnt lgkmcnt(0)
	v_add_f32_e32 v86, v76, v250
	v_add_f32_e32 v87, v77, v251
	v_add_f32_e32 v91, v78, v126
	v_add_f32_e32 v101, v79, v127
	v_mov_b32_e32 v72, v228
	v_mov_b32_e32 v73, v229
	v_mov_b32_e32 v74, v230
	v_mov_b32_e32 v75, v231
	v_mov_b32_e32 v79, v69
	v_cndmask_b32_e64 v78, v80, -v80, s[0:1]
	v_cndmask_b32_e64 v84, v84, -v84, s[0:1]
	v_cndmask_b32_e64 v86, v86, -v86, s[0:1]
	s_waitcnt vmcnt(5) lgkmcnt(0)
	v_mov_b32_e32 v76, v73
	v_cndmask_b32_e64 v73, v81, -v81, s[0:1]
	v_mov_b32_e32 v69, v73
	v_mov_b32_e32 v73, v75
	v_mov_b32_e32 v77, v74
	v_pk_mul_f32 v[80:81], v[68:69], v[72:73]
	v_mov_b32_e32 v72, v232
	v_mov_b32_e32 v73, v233
	v_mov_b32_e32 v74, v234
	v_mov_b32_e32 v75, v235
	v_cndmask_b32_e64 v68, v85, -v85, s[0:1]
	v_mov_b32_e32 v85, v71
	v_mov_b32_e32 v71, v68
	s_waitcnt vmcnt(5) lgkmcnt(0)
	v_mov_b32_e32 v82, v73
	v_mov_b32_e32 v73, v75
	v_pk_mul_f32 v[72:73], v[70:71], v[72:73]
	v_mov_b32_e32 v68, v236
	v_mov_b32_e32 v69, v237
	v_mov_b32_e32 v70, v238
	v_mov_b32_e32 v71, v239
	v_mov_b32_e32 v83, v74
	s_waitcnt vmcnt(5) lgkmcnt(0)
	v_mov_b32_e32 v74, v69
	v_cndmask_b32_e64 v69, v87, -v87, s[0:1]
	v_mov_b32_e32 v87, v65
	v_mov_b32_e32 v65, v69
	v_mov_b32_e32 v69, v71
	v_mov_b32_e32 v75, v70
	v_pk_mul_f32 v[64:65], v[64:65], v[68:69]
	v_mov_b32_e32 v68, v240
	v_mov_b32_e32 v69, v241
	v_mov_b32_e32 v70, v242
	v_mov_b32_e32 v71, v243
	v_pk_fma_f32 v[64:65], v[86:87], v[74:75], v[64:65]
	s_waitcnt vmcnt(5) lgkmcnt(0)
	v_mul_f32_e32 v66, v66, v68
	v_cndmask_b32_e64 v68, v91, -v91, s[0:1]
	v_mul_f32_e32 v92, v68, v69
	v_cndmask_b32_e64 v69, v101, -v101, s[0:1]
	v_mov_b32_e32 v68, v67
	v_pk_mul_f32 v[68:69], v[68:69], v[70:71]
	v_pk_fma_f32 v[70:71], v[84:85], v[82:83], v[72:73]
	v_mov_b32_e32 v67, v68
	v_mov_b32_e32 v93, v69
	v_pk_fma_f32 v[68:69], v[78:79], v[76:77], v[80:81]
	v_pk_add_f32 v[66:67], v[66:67], v[92:93]

;   DI void operator()(int mt, int nt, int wm, int wn, int r, int h, f32x16 (&acc)[WM][2]) const {
;     ...
;           if (ropemode != 0) {
;             const int pc = (ropemode == 1) ? (cc ^ 1) : (cc ^ 2);
;             const float4 p0 = *(const float4*)(T + lr * LD + pc * 8), p1 = *(const float4*)(T + lr * LD + pc * 8 + 4);
;             const float4 c0 = *(const float4*)(bias + nt * 128 + pc * 8), c1 = *(const float4*)(bias + nt * 128 + pc * 8 + 4);
;             const float pr[8] = {p0.x + c0.x, p0.y + c0.y, p0.z + c0.z, p0.w + c0.w, p1.x + c1.x, p1.y + c1.y, p1.z + c1.z, p1.w + c1.w};
;             const int tok = t - NCTX;
;             const int q = (ropemode == 1) ? (cc & 3) : ((cc & 7) >> 1);
;             const int pos = (q < 2) ? (tok >> 6) : (tok & 63);
;             const float2* tab = (ropemode == 1) ? (T32 + pos * 8) : (T64 + pos * 16 + (cc & 1) * 8);
;             const float sgn = (q & 1) ? 1.f : -1.f;
; #pragma unroll
;             for (int k = 0; k < 8; ++k) { const float2 cs = tab[k]; v[k] = v[k] * cs.x + sgn * pr[k] * cs.y; }
.LBB0_240:
	s_waitcnt vmcnt(1) lgkmcnt(1)
	v_add_f32_e32 v80, v84, v213
	v_add_f32_e32 v81, v85, v218
	v_add_f32_e32 v84, v86, v219
	v_add_f32_e32 v85, v87, v245
	s_waitcnt lgkmcnt(0)
	v_add_f32_e32 v86, v76, v250
	v_add_f32_e32 v87, v77, v251
	v_add_f32_e32 v91, v78, v126
	v_add_f32_e32 v160, v79, v127
	v_mov_b32_e32 v72, v112
	v_mov_b32_e32 v73, v113
	v_mov_b32_e32 v74, v114
	v_mov_b32_e32 v75, v115
	v_mov_b32_e32 v79, v69
	v_cndmask_b32_e64 v78, v80, -v80, s[0:1]
	v_cndmask_b32_e64 v84, v84, -v84, s[0:1]
	v_cndmask_b32_e64 v86, v86, -v86, s[0:1]
	s_waitcnt vmcnt(1) lgkmcnt(0)
	v_mov_b32_e32 v76, v73
	v_cndmask_b32_e64 v73, v81, -v81, s[0:1]
	v_mov_b32_e32 v69, v73
	v_mov_b32_e32 v73, v75
	v_mov_b32_e32 v77, v74
	v_pk_mul_f32 v[80:81], v[68:69], v[72:73]
	v_mov_b32_e32 v72, v116
	v_mov_b32_e32 v73, v117
	v_mov_b32_e32 v74, v118
	v_mov_b32_e32 v75, v119
	v_cndmask_b32_e64 v68, v85, -v85, s[0:1]
	v_mov_b32_e32 v85, v71
	v_mov_b32_e32 v71, v68
	s_waitcnt vmcnt(1) lgkmcnt(0)
	v_mov_b32_e32 v82, v73
	v_mov_b32_e32 v73, v75
	v_pk_mul_f32 v[72:73], v[70:71], v[72:73]
	v_mov_b32_e32 v68, v214
	v_mov_b32_e32 v69, v215
	v_mov_b32_e32 v70, v216
	v_mov_b32_e32 v71, v217
	v_mov_b32_e32 v83, v74
	s_waitcnt vmcnt(1) lgkmcnt(0)
	v_mov_b32_e32 v74, v69
	v_cndmask_b32_e64 v69, v87, -v87, s[0:1]
	v_mov_b32_e32 v87, v65
	v_mov_b32_e32 v65, v69
	v_mov_b32_e32 v69, v71
	v_mov_b32_e32 v75, v70
	v_pk_mul_f32 v[64:65], v[64:65], v[68:69]
	v_mov_b32_e32 v68, v246
	v_mov_b32_e32 v69, v247
	v_mov_b32_e32 v70, v248
	v_mov_b32_e32 v71, v249
	v_pk_fma_f32 v[64:65], v[86:87], v[74:75], v[64:65]
	s_waitcnt vmcnt(1) lgkmcnt(0)
	v_mul_f32_e32 v66, v66, v68
	v_cndmask_b32_e64 v68, v91, -v91, s[0:1]
	v_mul_f32_e32 v92, v68, v69
	v_cndmask_b32_e64 v69, v160, -v160, s[0:1]
	v_mov_b32_e32 v68, v67
	v_pk_mul_f32 v[68:69], v[68:69], v[70:71]
	v_pk_fma_f32 v[70:71], v[84:85], v[82:83], v[72:73]
	v_mov_b32_e32 v67, v68
	v_mov_b32_e32 v93, v69
	v_pk_fma_f32 v[68:69], v[78:79], v[76:77], v[80:81]
	v_pk_add_f32 v[66:67], v[66:67], v[92:93]

;   DI void operator()(int mt, int nt, int wm, int wn, int r, int h, f32x16 (&acc)[WM][2]) const {
;     ...
;           if (ropemode != 0) {
;             const int pc = (ropemode == 1) ? (cc ^ 1) : (cc ^ 2);
;             const float4 p0 = *(const float4*)(T + lr * LD + pc * 8), p1 = *(const float4*)(T + lr * LD + pc * 8 + 4);
;             const float4 c0 = *(const float4*)(bias + nt * 128 + pc * 8), c1 = *(const float4*)(bias + nt * 128 + pc * 8 + 4);
;             const float pr[8] = {p0.x + c0.x, p0.y + c0.y, p0.z + c0.z, p0.w + c0.w, p1.x + c1.x, p1.y + c1.y, p1.z + c1.z, p1.w + c1.w};
;             const int tok = t - NCTX;
;             const int q = (ropemode == 1) ? (cc & 3) : ((cc & 7) >> 1);
;             const int pos = (q < 2) ? (tok >> 6) : (tok & 63);
;             const float2* tab = (ropemode == 1) ? (T32 + pos * 8) : (T64 + pos * 16 + (cc & 1) * 8);
;             const float sgn = (q & 1) ? 1.f : -1.f;
; #pragma unroll
;             for (int k = 0; k < 8; ++k) { const float2 cs = tab[k]; v[k] = v[k] * cs.x + sgn * pr[k] * cs.y; }
.Lrp_l_1_1:
	global_load_dwordx4 v[228:231], v[120:121], off
	global_load_dwordx4 v[232:235], v[120:121], off offset:16
	global_load_dwordx4 v[236:239], v[120:121], off offset:32
	global_load_dwordx4 v[240:243], v[120:121], off offset:48
	s_waitcnt vmcnt(5) lgkmcnt(1)
	v_add_f32_e32 v16, v20, v213
	v_add_f32_e32 v17, v21, v218
	v_add_f32_e32 v20, v22, v219
	v_add_f32_e32 v21, v23, v245
	s_waitcnt lgkmcnt(0)
	v_add_f32_e32 v22, v12, v250
	v_add_f32_e32 v23, v13, v251
	v_add_f32_e32 v25, v14, v126
	v_add_f32_e32 v30, v15, v127
	v_mov_b32_e32 v8, v112
	v_mov_b32_e32 v9, v113
	v_mov_b32_e32 v10, v114
	v_mov_b32_e32 v11, v115
	v_mov_b32_e32 v15, v5
	v_cndmask_b32_e64 v14, v16, -v16, s[0:1]
	v_cndmask_b32_e64 v20, v20, -v20, s[0:1]
	v_cndmask_b32_e64 v22, v22, -v22, s[0:1]
	s_waitcnt vmcnt(5) lgkmcnt(0)
	v_mov_b32_e32 v12, v9
	v_cndmask_b32_e64 v9, v17, -v17, s[0:1]
	v_mov_b32_e32 v5, v9
	v_mov_b32_e32 v9, v11
	v_mov_b32_e32 v13, v10
	v_pk_mul_f32 v[16:17], v[4:5], v[8:9]
	v_mov_b32_e32 v8, v116
	v_mov_b32_e32 v9, v117
	v_mov_b32_e32 v10, v118
	v_mov_b32_e32 v11, v119
	v_cndmask_b32_e64 v4, v21, -v21, s[0:1]
	v_mov_b32_e32 v21, v7
	v_mov_b32_e32 v7, v4
	s_waitcnt vmcnt(5) lgkmcnt(0)
	v_mov_b32_e32 v18, v9
	v_mov_b32_e32 v9, v11
	v_pk_mul_f32 v[8:9], v[6:7], v[8:9]
	v_mov_b32_e32 v4, v214
	v_mov_b32_e32 v5, v215
	v_mov_b32_e32 v6, v216
	v_mov_b32_e32 v7, v217
	v_mov_b32_e32 v19, v10
	s_waitcnt vmcnt(5) lgkmcnt(0)
	v_mov_b32_e32 v10, v5
	v_cndmask_b32_e64 v5, v23, -v23, s[0:1]
	v_mov_b32_e32 v23, v1
	v_mov_b32_e32 v1, v5
	v_mov_b32_e32 v5, v7
	v_mov_b32_e32 v11, v6
	v_pk_mul_f32 v[0:1], v[0:1], v[4:5]
	v_mov_b32_e32 v4, v246
	v_mov_b32_e32 v5, v247
	v_mov_b32_e32 v6, v248
	v_mov_b32_e32 v7, v249
	v_pk_fma_f32 v[0:1], v[22:23], v[10:11], v[0:1]
	s_waitcnt vmcnt(5) lgkmcnt(0)
	v_mul_f32_e32 v2, v2, v4
	v_cndmask_b32_e64 v4, v25, -v25, s[0:1]
	v_mul_f32_e32 v26, v4, v5
	v_cndmask_b32_e64 v5, v30, -v30, s[0:1]
	v_mov_b32_e32 v4, v3
	v_pk_mul_f32 v[4:5], v[4:5], v[6:7]
	v_pk_fma_f32 v[6:7], v[20:21], v[18:19], v[8:9]
	v_mov_b32_e32 v3, v4
	v_mov_b32_e32 v27, v5
	v_pk_fma_f32 v[4:5], v[14:15], v[12:13], v[16:17]
	v_pk_add_f32 v[2:3], v[2:3], v[26:27]

;   DI void operator()(int mt, int nt, int wm, int wn, int r, int h, f32x16 (&acc)[WM][2]) const {
;     ...
;           if (ropemode != 0) {
;             const int pc = (ropemode == 1) ? (cc ^ 1) : (cc ^ 2);
;             const float4 p0 = *(const float4*)(T + lr * LD + pc * 8), p1 = *(const float4*)(T + lr * LD + pc * 8 + 4);
;             const float4 c0 = *(const float4*)(bias + nt * 128 + pc * 8), c1 = *(const float4*)(bias + nt * 128 + pc * 8 + 4);
;             const float pr[8] = {p0.x + c0.x, p0.y + c0.y, p0.z + c0.z, p0.w + c0.w, p1.x + c1.x, p1.y + c1.y, p1.z + c1.z, p1.w + c1.w};
;             const int tok = t - NCTX;
;             const int q = (ropemode == 1) ? (cc & 3) : ((cc & 7) >> 1);
;             const int pos = (q < 2) ? (tok >> 6) : (tok & 63);
;             const float2* tab = (ropemode == 1) ? (T32 + pos * 8) : (T64 + pos * 16 + (cc & 1) * 8);
;             const float sgn = (q & 1) ? 1.f : -1.f;
; #pragma unroll
;             for (int k = 0; k < 8; ++k) { const float2 cs = tab[k]; v[k] = v[k] * cs.x + sgn * pr[k] * cs.y; }
.Lrp_l_1_2:
	global_load_dwordx4 v[112:115], v[120:121], off
	global_load_dwordx4 v[116:119], v[120:121], off offset:16
	global_load_dwordx4 v[214:217], v[120:121], off offset:32
	global_load_dwordx4 v[246:249], v[120:121], off offset:48
	s_waitcnt vmcnt(5) lgkmcnt(1)
	v_add_f32_e32 v16, v20, v213
	v_add_f32_e32 v17, v21, v218
	v_add_f32_e32 v20, v22, v219
	v_add_f32_e32 v21, v23, v245
	s_waitcnt lgkmcnt(0)
	v_add_f32_e32 v22, v12, v250
	v_add_f32_e32 v23, v13, v251
	v_add_f32_e32 v25, v14, v126
	v_add_f32_e32 v31, v15, v127
	v_mov_b32_e32 v8, v228
	v_mov_b32_e32 v9, v229
	v_mov_b32_e32 v10, v230
	v_mov_b32_e32 v11, v231
	v_mov_b32_e32 v15, v5
	v_cndmask_b32_e64 v14, v16, -v16, s[0:1]
	v_cndmask_b32_e64 v20, v20, -v20, s[0:1]
	v_cndmask_b32_e64 v22, v22, -v22, s[0:1]
	s_waitcnt vmcnt(5) lgkmcnt(0)
	v_mov_b32_e32 v12, v9
	v_cndmask_b32_e64 v9, v17, -v17, s[0:1]
	v_mov_b32_e32 v5, v9
	v_mov_b32_e32 v9, v11
	v_mov_b32_e32 v13, v10
	v_pk_mul_f32 v[16:17], v[4:5], v[8:9]
	v_mov_b32_e32 v8, v232
	v_mov_b32_e32 v9, v233
	v_mov_b32_e32 v10, v234
	v_mov_b32_e32 v11, v235
	v_cndmask_b32_e64 v4, v21, -v21, s[0:1]
	v_mov_b32_e32 v21, v7
	v_mov_b32_e32 v7, v4
	s_waitcnt vmcnt(5) lgkmcnt(0)
	v_mov_b32_e32 v18, v9
	v_mov_b32_e32 v9, v11
	v_pk_mul_f32 v[8:9], v[6:7], v[8:9]
	v_mov_b32_e32 v4, v236
	v_mov_b32_e32 v5, v237
	v_mov_b32_e32 v6, v238
	v_mov_b32_e32 v7, v239
	v_mov_b32_e32 v19, v10
	s_waitcnt vmcnt(5) lgkmcnt(0)
	v_mov_b32_e32 v10, v5
	v_cndmask_b32_e64 v5, v23, -v23, s[0:1]
	v_mov_b32_e32 v23, v1
	v_mov_b32_e32 v1, v5
	v_mov_b32_e32 v5, v7
	v_mov_b32_e32 v11, v6
	v_pk_mul_f32 v[0:1], v[0:1], v[4:5]
	v_mov_b32_e32 v4, v240
	v_mov_b32_e32 v5, v241
	v_mov_b32_e32 v6, v242
	v_mov_b32_e32 v7, v243
	v_pk_fma_f32 v[0:1], v[22:23], v[10:11], v[0:1]
	s_waitcnt vmcnt(5) lgkmcnt(0)
	v_mul_f32_e32 v2, v2, v4
	v_cndmask_b32_e64 v4, v25, -v25, s[0:1]
	v_mul_f32_e32 v26, v4, v5
	v_cndmask_b32_e64 v5, v31, -v31, s[0:1]
	v_mov_b32_e32 v4, v3
	v_pk_mul_f32 v[4:5], v[4:5], v[6:7]
	v_pk_fma_f32 v[6:7], v[20:21], v[18:19], v[8:9]
	v_mov_b32_e32 v3, v4
	v_mov_b32_e32 v27, v5
	v_pk_fma_f32 v[4:5], v[14:15], v[12:13], v[16:17]
	v_pk_add_f32 v[2:3], v[2:3], v[26:27]

;   DI void operator()(int mt, int nt, int wm, int wn, int r, int h, f32x16 (&acc)[WM][2]) const {
;     ...
;           if (ropemode != 0) {
;             const int pc = (ropemode == 1) ? (cc ^ 1) : (cc ^ 2);
;             const float4 p0 = *(const float4*)(T + lr * LD + pc * 8), p1 = *(const float4*)(T + lr * LD + pc * 8 + 4);
;             const float4 c0 = *(const float4*)(bias + nt * 128 + pc * 8), c1 = *(const float4*)(bias + nt * 128 + pc * 8 + 4);
;             const float pr[8] = {p0.x + c0.x, p0.y + c0.y, p0.z + c0.z, p0.w + c0.w, p1.x + c1.x, p1.y + c1.y, p1.z + c1.z, p1.w + c1.w};
;             const int tok = t - NCTX;
;             const int q = (ropemode == 1) ? (cc & 3) : ((cc & 7) >> 1);
;             const int pos = (q < 2) ? (tok >> 6) : (tok & 63);
;             const float2* tab = (ropemode == 1) ? (T32 + pos * 8) : (T64 + pos * 16 + (cc & 1) * 8);
;             const float sgn = (q & 1) ? 1.f : -1.f;
; #pragma unroll
;             for (int k = 0; k < 8; ++k) { const float2 cs = tab[k]; v[k] = v[k] * cs.x + sgn * pr[k] * cs.y; }
.Lrp_l_1_3:
	global_load_dwordx4 v[228:231], v[120:121], off
	global_load_dwordx4 v[232:235], v[120:121], off offset:16
	global_load_dwordx4 v[236:239], v[120:121], off offset:32
	global_load_dwordx4 v[240:243], v[120:121], off offset:48
	s_waitcnt vmcnt(5) lgkmcnt(1)
	v_add_f32_e32 v16, v20, v213
	v_add_f32_e32 v17, v21, v218
	v_add_f32_e32 v20, v22, v219
	v_add_f32_e32 v21, v23, v245
	s_waitcnt lgkmcnt(0)
	v_add_f32_e32 v22, v12, v250
	v_add_f32_e32 v23, v13, v251
	v_add_f32_e32 v25, v14, v126
	v_add_f32_e32 v32, v15, v127
	v_mov_b32_e32 v8, v112
	v_mov_b32_e32 v9, v113
	v_mov_b32_e32 v10, v114
	v_mov_b32_e32 v11, v115
	v_mov_b32_e32 v15, v5
	v_cndmask_b32_e64 v14, v16, -v16, s[0:1]
	v_cndmask_b32_e64 v20, v20, -v20, s[0:1]
	v_cndmask_b32_e64 v22, v22, -v22, s[0:1]
	s_waitcnt vmcnt(5) lgkmcnt(0)
	v_mov_b32_e32 v12, v9
	v_cndmask_b32_e64 v9, v17, -v17, s[0:1]
	v_mov_b32_e32 v5, v9
	v_mov_b32_e32 v9, v11
	v_mov_b32_e32 v13, v10
	v_pk_mul_f32 v[16:17], v[4:5], v[8:9]
	v_mov_b32_e32 v8, v116
	v_mov_b32_e32 v9, v117
	v_mov_b32_e32 v10, v118
	v_mov_b32_e32 v11, v119
	v_cndmask_b32_e64 v4, v21, -v21, s[0:1]
	v_mov_b32_e32 v21, v7
	v_mov_b32_e32 v7, v4
	s_waitcnt vmcnt(5) lgkmcnt(0)
	v_mov_b32_e32 v18, v9
	v_mov_b32_e32 v9, v11
	v_pk_mul_f32 v[8:9], v[6:7], v[8:9]
	v_mov_b32_e32 v4, v214
	v_mov_b32_e32 v5, v215
	v_mov_b32_e32 v6, v216
	v_mov_b32_e32 v7, v217
	v_mov_b32_e32 v19, v10
	s_waitcnt vmcnt(5) lgkmcnt(0)
	v_mov_b32_e32 v10, v5
	v_cndmask_b32_e64 v5, v23, -v23, s[0:1]
	v_mov_b32_e32 v23, v1
	v_mov_b32_e32 v1, v5
	v_mov_b32_e32 v5, v7
	v_mov_b32_e32 v11, v6
	v_pk_mul_f32 v[0:1], v[0:1], v[4:5]
	v_mov_b32_e32 v4, v246
	v_mov_b32_e32 v5, v247
	v_mov_b32_e32 v6, v248
	v_mov_b32_e32 v7, v249
	v_pk_fma_f32 v[0:1], v[22:23], v[10:11], v[0:1]
	s_waitcnt vmcnt(5) lgkmcnt(0)
	v_mul_f32_e32 v2, v2, v4
	v_cndmask_b32_e64 v4, v25, -v25, s[0:1]
	v_mul_f32_e32 v26, v4, v5
	v_cndmask_b32_e64 v5, v32, -v32, s[0:1]
	v_mov_b32_e32 v4, v3
	v_pk_mul_f32 v[4:5], v[4:5], v[6:7]
	v_pk_fma_f32 v[6:7], v[20:21], v[18:19], v[8:9]
	v_mov_b32_e32 v3, v4
	v_mov_b32_e32 v27, v5
	v_pk_fma_f32 v[4:5], v[14:15], v[12:13], v[16:17]
	v_pk_add_f32 v[2:3], v[2:3], v[26:27]

;   DI void operator()(int mt, int nt, int wm, int wn, int r, int h, f32x16 (&acc)[WM][2]) const {
;     ...
;           if (ropemode != 0) {
;             const int pc = (ropemode == 1) ? (cc ^ 1) : (cc ^ 2);
;             const float4 p0 = *(const float4*)(T + lr * LD + pc * 8), p1 = *(const float4*)(T + lr * LD + pc * 8 + 4);
;             const float4 c0 = *(const float4*)(bias + nt * 128 + pc * 8), c1 = *(const float4*)(bias + nt * 128 + pc * 8 + 4);
;             const float pr[8] = {p0.x + c0.x, p0.y + c0.y, p0.z + c0.z, p0.w + c0.w, p1.x + c1.x, p1.y + c1.y, p1.z + c1.z, p1.w + c1.w};
;             const int tok = t - NCTX;
;             const int q = (ropemode == 1) ? (cc & 3) : ((cc & 7) >> 1);
;             const int pos = (q < 2) ? (tok >> 6) : (tok & 63);
;             const float2* tab = (ropemode == 1) ? (T32 + pos * 8) : (T64 + pos * 16 + (cc & 1) * 8);
;             const float sgn = (q & 1) ? 1.f : -1.f;
; #pragma unroll
;             for (int k = 0; k < 8; ++k) { const float2 cs = tab[k]; v[k] = v[k] * cs.x + sgn * pr[k] * cs.y; }
.Lrp_l_1_4:
	global_load_dwordx4 v[112:115], v[120:121], off
	global_load_dwordx4 v[116:119], v[120:121], off offset:16
	global_load_dwordx4 v[214:217], v[120:121], off offset:32
	global_load_dwordx4 v[246:249], v[120:121], off offset:48
	s_waitcnt vmcnt(5) lgkmcnt(1)
	v_add_f32_e32 v16, v20, v213
	v_add_f32_e32 v17, v21, v218
	v_add_f32_e32 v20, v22, v219
	v_add_f32_e32 v21, v23, v245
	s_waitcnt lgkmcnt(0)
	v_add_f32_e32 v22, v12, v250
	v_add_f32_e32 v23, v13, v251
	v_add_f32_e32 v25, v14, v126
	v_add_f32_e32 v33, v15, v127
	v_mov_b32_e32 v8, v228
	v_mov_b32_e32 v9, v229
	v_mov_b32_e32 v10, v230
	v_mov_b32_e32 v11, v231
	v_mov_b32_e32 v15, v5
	v_cndmask_b32_e64 v14, v16, -v16, s[0:1]
	v_cndmask_b32_e64 v20, v20, -v20, s[0:1]
	v_cndmask_b32_e64 v22, v22, -v22, s[0:1]
	s_waitcnt vmcnt(5) lgkmcnt(0)
	v_mov_b32_e32 v12, v9
	v_cndmask_b32_e64 v9, v17, -v17, s[0:1]
	v_mov_b32_e32 v5, v9
	v_mov_b32_e32 v9, v11
	v_mov_b32_e32 v13, v10
	v_pk_mul_f32 v[16:17], v[4:5], v[8:9]
	v_mov_b32_e32 v8, v232
	v_mov_b32_e32 v9, v233
	v_mov_b32_e32 v10, v234
	v_mov_b32_e32 v11, v235
	v_cndmask_b32_e64 v4, v21, -v21, s[0:1]
	v_mov_b32_e32 v21, v7
	v_mov_b32_e32 v7, v4
	s_waitcnt vmcnt(5) lgkmcnt(0)
	v_mov_b32_e32 v18, v9
	v_mov_b32_e32 v9, v11
	v_pk_mul_f32 v[8:9], v[6:7], v[8:9]
	v_mov_b32_e32 v4, v236
	v_mov_b32_e32 v5, v237
	v_mov_b32_e32 v6, v238
	v_mov_b32_e32 v7, v239
	v_mov_b32_e32 v19, v10
	s_waitcnt vmcnt(5) lgkmcnt(0)
	v_mov_b32_e32 v10, v5
	v_cndmask_b32_e64 v5, v23, -v23, s[0:1]
	v_mov_b32_e32 v23, v1
	v_mov_b32_e32 v1, v5
	v_mov_b32_e32 v5, v7
	v_mov_b32_e32 v11, v6
	v_pk_mul_f32 v[0:1], v[0:1], v[4:5]
	v_mov_b32_e32 v4, v240
	v_mov_b32_e32 v5, v241
	v_mov_b32_e32 v6, v242
	v_mov_b32_e32 v7, v243
	v_pk_fma_f32 v[0:1], v[22:23], v[10:11], v[0:1]
	s_waitcnt vmcnt(5) lgkmcnt(0)
	v_mul_f32_e32 v2, v2, v4
	v_cndmask_b32_e64 v4, v25, -v25, s[0:1]
	v_mul_f32_e32 v26, v4, v5
	v_cndmask_b32_e64 v5, v33, -v33, s[0:1]
	v_mov_b32_e32 v4, v3
	v_pk_mul_f32 v[4:5], v[4:5], v[6:7]
	v_pk_fma_f32 v[6:7], v[20:21], v[18:19], v[8:9]
	v_mov_b32_e32 v3, v4
	v_mov_b32_e32 v27, v5
	v_pk_fma_f32 v[4:5], v[14:15], v[12:13], v[16:17]
	v_pk_add_f32 v[2:3], v[2:3], v[26:27]

;   DI void operator()(int mt, int nt, int wm, int wn, int r, int h, f32x16 (&acc)[WM][2]) const {
;     ...
;           if (ropemode != 0) {
;             const int pc = (ropemode == 1) ? (cc ^ 1) : (cc ^ 2);
;             const float4 p0 = *(const float4*)(T + lr * LD + pc * 8), p1 = *(const float4*)(T + lr * LD + pc * 8 + 4);
;             const float4 c0 = *(const float4*)(bias + nt * 128 + pc * 8), c1 = *(const float4*)(bias + nt * 128 + pc * 8 + 4);
;             const float pr[8] = {p0.x + c0.x, p0.y + c0.y, p0.z + c0.z, p0.w + c0.w, p1.x + c1.x, p1.y + c1.y, p1.z + c1.z, p1.w + c1.w};
;             const int tok = t - NCTX;
;             const int q = (ropemode == 1) ? (cc & 3) : ((cc & 7) >> 1);
;             const int pos = (q < 2) ? (tok >> 6) : (tok & 63);
;             const float2* tab = (ropemode == 1) ? (T32 + pos * 8) : (T64 + pos * 16 + (cc & 1) * 8);
;             const float sgn = (q & 1) ? 1.f : -1.f;
; #pragma unroll
;             for (int k = 0; k < 8; ++k) { const float2 cs = tab[k]; v[k] = v[k] * cs.x + sgn * pr[k] * cs.y; }
.Lrp_l_1_5:
	global_load_dwordx4 v[228:231], v[120:121], off
	global_load_dwordx4 v[232:235], v[120:121], off offset:16
	global_load_dwordx4 v[236:239], v[120:121], off offset:32
	global_load_dwordx4 v[240:243], v[120:121], off offset:48
	s_waitcnt vmcnt(5) lgkmcnt(1)
	v_add_f32_e32 v16, v20, v213
	v_add_f32_e32 v17, v21, v218
	v_add_f32_e32 v20, v22, v219
	v_add_f32_e32 v21, v23, v245
	s_waitcnt lgkmcnt(0)
	v_add_f32_e32 v22, v12, v250
	v_add_f32_e32 v23, v13, v251
	v_add_f32_e32 v25, v14, v126
	v_add_f32_e32 v34, v15, v127
	v_mov_b32_e32 v8, v112
	v_mov_b32_e32 v9, v113
	v_mov_b32_e32 v10, v114
	v_mov_b32_e32 v11, v115
	v_mov_b32_e32 v15, v5
	v_cndmask_b32_e64 v14, v16, -v16, s[0:1]
	v_cndmask_b32_e64 v20, v20, -v20, s[0:1]
	v_cndmask_b32_e64 v22, v22, -v22, s[0:1]
	s_waitcnt vmcnt(5) lgkmcnt(0)
	v_mov_b32_e32 v12, v9
	v_cndmask_b32_e64 v9, v17, -v17, s[0:1]
	v_mov_b32_e32 v5, v9
	v_mov_b32_e32 v9, v11
	v_mov_b32_e32 v13, v10
	v_pk_mul_f32 v[16:17], v[4:5], v[8:9]
	v_mov_b32_e32 v8, v116
	v_mov_b32_e32 v9, v117
	v_mov_b32_e32 v10, v118
	v_mov_b32_e32 v11, v119
	v_cndmask_b32_e64 v4, v21, -v21, s[0:1]
	v_mov_b32_e32 v21, v7
	v_mov_b32_e32 v7, v4
	s_waitcnt vmcnt(5) lgkmcnt(0)
	v_mov_b32_e32 v18, v9
	v_mov_b32_e32 v9, v11
	v_pk_mul_f32 v[8:9], v[6:7], v[8:9]
	v_mov_b32_e32 v4, v214
	v_mov_b32_e32 v5, v215
	v_mov_b32_e32 v6, v216
	v_mov_b32_e32 v7, v217
	v_mov_b32_e32 v19, v10
	s_waitcnt vmcnt(5) lgkmcnt(0)
	v_mov_b32_e32 v10, v5
	v_cndmask_b32_e64 v5, v23, -v23, s[0:1]
	v_mov_b32_e32 v23, v1
	v_mov_b32_e32 v1, v5
	v_mov_b32_e32 v5, v7
	v_mov_b32_e32 v11, v6
	v_pk_mul_f32 v[0:1], v[0:1], v[4:5]
	v_mov_b32_e32 v4, v246
	v_mov_b32_e32 v5, v247
	v_mov_b32_e32 v6, v248
	v_mov_b32_e32 v7, v249
	v_pk_fma_f32 v[0:1], v[22:23], v[10:11], v[0:1]
	s_waitcnt vmcnt(5) lgkmcnt(0)
	v_mul_f32_e32 v2, v2, v4
	v_cndmask_b32_e64 v4, v25, -v25, s[0:1]
	v_mul_f32_e32 v26, v4, v5
	v_cndmask_b32_e64 v5, v34, -v34, s[0:1]
	v_mov_b32_e32 v4, v3
	v_pk_mul_f32 v[4:5], v[4:5], v[6:7]
	v_pk_fma_f32 v[6:7], v[20:21], v[18:19], v[8:9]
	v_mov_b32_e32 v3, v4
	v_mov_b32_e32 v27, v5
	v_pk_fma_f32 v[4:5], v[14:15], v[12:13], v[16:17]
	v_pk_add_f32 v[2:3], v[2:3], v[26:27]

;   DI void operator()(int mt, int nt, int wm, int wn, int r, int h, f32x16 (&acc)[WM][2]) const {
;     ...
;           if (ropemode != 0) {
;             const int pc = (ropemode == 1) ? (cc ^ 1) : (cc ^ 2);
;             const float4 p0 = *(const float4*)(T + lr * LD + pc * 8), p1 = *(const float4*)(T + lr * LD + pc * 8 + 4);
;             const float4 c0 = *(const float4*)(bias + nt * 128 + pc * 8), c1 = *(const float4*)(bias + nt * 128 + pc * 8 + 4);
;             const float pr[8] = {p0.x + c0.x, p0.y + c0.y, p0.z + c0.z, p0.w + c0.w, p1.x + c1.x, p1.y + c1.y, p1.z + c1.z, p1.w + c1.w};
;             const int tok = t - NCTX;
;             const int q = (ropemode == 1) ? (cc & 3) : ((cc & 7) >> 1);
;             const int pos = (q < 2) ? (tok >> 6) : (tok & 63);
;             const float2* tab = (ropemode == 1) ? (T32 + pos * 8) : (T64 + pos * 16 + (cc & 1) * 8);
;             const float sgn = (q & 1) ? 1.f : -1.f;
; #pragma unroll
;             for (int k = 0; k < 8; ++k) { const float2 cs = tab[k]; v[k] = v[k] * cs.x + sgn * pr[k] * cs.y; }
.Lrp_l_1_6:
	global_load_dwordx4 v[112:115], v[120:121], off
	global_load_dwordx4 v[116:119], v[120:121], off offset:16
	global_load_dwordx4 v[214:217], v[120:121], off offset:32
	global_load_dwordx4 v[246:249], v[120:121], off offset:48
	s_waitcnt vmcnt(5) lgkmcnt(1)
	v_add_f32_e32 v16, v20, v213
	v_add_f32_e32 v17, v21, v218
	v_add_f32_e32 v20, v22, v219
	v_add_f32_e32 v21, v23, v245
	s_waitcnt lgkmcnt(0)
	v_add_f32_e32 v22, v12, v250
	v_add_f32_e32 v23, v13, v251
	v_add_f32_e32 v25, v14, v126
	v_add_f32_e32 v35, v15, v127
	v_mov_b32_e32 v8, v228
	v_mov_b32_e32 v9, v229
	v_mov_b32_e32 v10, v230
	v_mov_b32_e32 v11, v231
	v_mov_b32_e32 v15, v5
	v_cndmask_b32_e64 v14, v16, -v16, s[0:1]
	v_cndmask_b32_e64 v20, v20, -v20, s[0:1]
	v_cndmask_b32_e64 v22, v22, -v22, s[0:1]
	s_waitcnt vmcnt(5) lgkmcnt(0)
	v_mov_b32_e32 v12, v9
	v_cndmask_b32_e64 v9, v17, -v17, s[0:1]
	v_mov_b32_e32 v5, v9
	v_mov_b32_e32 v9, v11
	v_mov_b32_e32 v13, v10
	v_pk_mul_f32 v[16:17], v[4:5], v[8:9]
	v_mov_b32_e32 v8, v232
	v_mov_b32_e32 v9, v233
	v_mov_b32_e32 v10, v234
	v_mov_b32_e32 v11, v235
	v_cndmask_b32_e64 v4, v21, -v21, s[0:1]
	v_mov_b32_e32 v21, v7
	v_mov_b32_e32 v7, v4
	s_waitcnt vmcnt(5) lgkmcnt(0)
	v_mov_b32_e32 v18, v9
	v_mov_b32_e32 v9, v11
	v_pk_mul_f32 v[8:9], v[6:7], v[8:9]
	v_mov_b32_e32 v4, v236
	v_mov_b32_e32 v5, v237
	v_mov_b32_e32 v6, v238
	v_mov_b32_e32 v7, v239
	v_mov_b32_e32 v19, v10
	s_waitcnt vmcnt(5) lgkmcnt(0)
	v_mov_b32_e32 v10, v5
	v_cndmask_b32_e64 v5, v23, -v23, s[0:1]
	v_mov_b32_e32 v23, v1
	v_mov_b32_e32 v1, v5
	v_mov_b32_e32 v5, v7
	v_mov_b32_e32 v11, v6
	v_pk_mul_f32 v[0:1], v[0:1], v[4:5]
	v_mov_b32_e32 v4, v240
	v_mov_b32_e32 v5, v241
	v_mov_b32_e32 v6, v242
	v_mov_b32_e32 v7, v243
	v_pk_fma_f32 v[0:1], v[22:23], v[10:11], v[0:1]
	s_waitcnt vmcnt(5) lgkmcnt(0)
	v_mul_f32_e32 v2, v2, v4
	v_cndmask_b32_e64 v4, v25, -v25, s[0:1]
	v_mul_f32_e32 v26, v4, v5
	v_cndmask_b32_e64 v5, v35, -v35, s[0:1]
	v_mov_b32_e32 v4, v3
	v_pk_mul_f32 v[4:5], v[4:5], v[6:7]
	v_pk_fma_f32 v[6:7], v[20:21], v[18:19], v[8:9]
	v_mov_b32_e32 v3, v4
	v_mov_b32_e32 v27, v5
	v_pk_fma_f32 v[4:5], v[14:15], v[12:13], v[16:17]
	v_pk_add_f32 v[2:3], v[2:3], v[26:27]

;   DI void operator()(int mt, int nt, int wm, int wn, int r, int h, f32x16 (&acc)[WM][2]) const {
;     ...
;           if (ropemode != 0) {
;             const int pc = (ropemode == 1) ? (cc ^ 1) : (cc ^ 2);
;             const float4 p0 = *(const float4*)(T + lr * LD + pc * 8), p1 = *(const float4*)(T + lr * LD + pc * 8 + 4);
;             const float4 c0 = *(const float4*)(bias + nt * 128 + pc * 8), c1 = *(const float4*)(bias + nt * 128 + pc * 8 + 4);
;             const float pr[8] = {p0.x + c0.x, p0.y + c0.y, p0.z + c0.z, p0.w + c0.w, p1.x + c1.x, p1.y + c1.y, p1.z + c1.z, p1.w + c1.w};
;             const int tok = t - NCTX;
;             const int q = (ropemode == 1) ? (cc & 3) : ((cc & 7) >> 1);
;             const int pos = (q < 2) ? (tok >> 6) : (tok & 63);
;             const float2* tab = (ropemode == 1) ? (T32 + pos * 8) : (T64 + pos * 16 + (cc & 1) * 8);
;             const float sgn = (q & 1) ? 1.f : -1.f;
; #pragma unroll
;             for (int k = 0; k < 8; ++k) { const float2 cs = tab[k]; v[k] = v[k] * cs.x + sgn * pr[k] * cs.y; }
.LBB0_350:
	s_waitcnt vmcnt(1) lgkmcnt(1)
	v_add_f32_e32 v16, v20, v213
	v_add_f32_e32 v17, v21, v218
	v_add_f32_e32 v20, v22, v219
	v_add_f32_e32 v21, v23, v245
	s_waitcnt lgkmcnt(0)
	v_add_f32_e32 v22, v12, v250
	v_add_f32_e32 v23, v13, v251
	v_add_f32_e32 v25, v14, v126
	v_add_f32_e32 v36, v15, v127
	v_mov_b32_e32 v8, v112
	v_mov_b32_e32 v9, v113
	v_mov_b32_e32 v10, v114
	v_mov_b32_e32 v11, v115
	v_mov_b32_e32 v15, v5
	v_cndmask_b32_e64 v14, v16, -v16, s[0:1]
	v_cndmask_b32_e64 v20, v20, -v20, s[0:1]
	v_cndmask_b32_e64 v22, v22, -v22, s[0:1]
	s_waitcnt vmcnt(1) lgkmcnt(0)
	v_mov_b32_e32 v12, v9
	v_cndmask_b32_e64 v9, v17, -v17, s[0:1]
	v_mov_b32_e32 v5, v9
	v_mov_b32_e32 v9, v11
	v_mov_b32_e32 v13, v10
	v_pk_mul_f32 v[16:17], v[4:5], v[8:9]
	v_mov_b32_e32 v8, v116
	v_mov_b32_e32 v9, v117
	v_mov_b32_e32 v10, v118
	v_mov_b32_e32 v11, v119
	v_cndmask_b32_e64 v4, v21, -v21, s[0:1]
	v_mov_b32_e32 v21, v7
	v_mov_b32_e32 v7, v4
	s_waitcnt vmcnt(1) lgkmcnt(0)
	v_mov_b32_e32 v18, v9
	v_mov_b32_e32 v9, v11
	v_pk_mul_f32 v[8:9], v[6:7], v[8:9]
	v_mov_b32_e32 v4, v214
	v_mov_b32_e32 v5, v215
	v_mov_b32_e32 v6, v216
	v_mov_b32_e32 v7, v217
	v_mov_b32_e32 v19, v10
	s_waitcnt vmcnt(1) lgkmcnt(0)
	v_mov_b32_e32 v10, v5
	v_cndmask_b32_e64 v5, v23, -v23, s[0:1]
	v_mov_b32_e32 v23, v1
	v_mov_b32_e32 v1, v5
	v_mov_b32_e32 v5, v7
	v_mov_b32_e32 v11, v6
	v_pk_mul_f32 v[0:1], v[0:1], v[4:5]
	v_mov_b32_e32 v4, v246
	v_mov_b32_e32 v5, v247
	v_mov_b32_e32 v6, v248
	v_mov_b32_e32 v7, v249
	v_pk_fma_f32 v[0:1], v[22:23], v[10:11], v[0:1]
	s_waitcnt vmcnt(1) lgkmcnt(0)
	v_mul_f32_e32 v2, v2, v4
	v_cndmask_b32_e64 v4, v25, -v25, s[0:1]
	v_mul_f32_e32 v26, v4, v5
	v_cndmask_b32_e64 v5, v36, -v36, s[0:1]
	v_mov_b32_e32 v4, v3
	v_pk_mul_f32 v[4:5], v[4:5], v[6:7]
	v_pk_fma_f32 v[6:7], v[20:21], v[18:19], v[8:9]
	v_mov_b32_e32 v3, v4
	v_mov_b32_e32 v27, v5
	v_pk_fma_f32 v[4:5], v[14:15], v[12:13], v[16:17]
	v_pk_add_f32 v[2:3], v[2:3], v[26:27]
